# GEMM tile prologue: previous tile's epilogue stores no longer drained (vmcnt(0)) before the first K-slice DMAs; stores/loads GLOBAL-encoded
# speedup vs baseline: 1.0083x; 1.0055x over previous
.LBB0_571:
	v_mov_b32_e32 v130, v154
	s_lshl_b32 s40, s43, 8
	v_ashrrev_i32_e32 v0, 31, v130
	v_lshrrev_b32_e32 v0, 26, v0
	v_add_u32_e32 v0, v130, v0
	v_ashrrev_i32_e32 v1, 6, v0
	v_bfe_i32 v0, v130, 27, 1
	v_lshlrev_b32_e32 v20, 4, v130
	v_lshrrev_b32_e32 v0, 22, v0
	v_add_u32_e32 v0, v20, v0
	v_and_b32_e32 v0, 0xfffffc00, v0
	v_sub_u32_e32 v0, v20, v0
	v_lshrrev_b32_e32 v2, 4, v0
	v_bitop3_b32 v2, v2, v0, 32 bitop3:0x6c
	v_ashrrev_i32_e32 v0, 31, v0
	v_lshrrev_b32_e32 v0, 26, v0
	v_lshlrev_b32_e32 v3, 3, v1
	v_add_u32_e32 v0, v2, v0
	v_and_b32_e32 v3, -16, v3
	v_ashrrev_i32_e32 v4, 6, v0
	v_add_u32_e32 v0, v4, v3
	v_mul_i32_i24_e32 v3, 64, v4
	s_ashr_i32 s41, s40, 31
	v_lshlrev_b32_e32 v1, 5, v1
	v_sub_u32_e32 v2, v2, v3
	s_lshl_b32 s42, s42, 8
	s_lshl_b64 s[44:45], s[40:41], 11
	v_and_b32_e32 v1, 32, v1
	v_ashrrev_i16_sdwa v2, v144, sext(v2) dst_sel:DWORD dst_unused:UNUSED_PAD src0_sel:DWORD src1_sel:BYTE_0
	s_add_u32 s46, s51, s44
	v_add_u32_sdwa v2, v1, sext(v2) dst_sel:DWORD dst_unused:UNUSED_PAD src0_sel:DWORD src1_sel:WORD_0
	v_ashrrev_i32_e32 v1, 31, v0
	s_addc_u32 s47, s52, s45
	v_lshlrev_b64 v[0:1], 11, v[0:1]
	v_ashrrev_i32_e32 v3, 31, v2
	v_lshl_add_u64 v[4:5], s[46:47], 0, v[0:1]
	v_lshlrev_b64 v[2:3], 1, v[2:3]
	v_add_u32_e32 v21, 0x2000, v20
	v_lshl_add_u64 v[8:9], v[4:5], 0, v[2:3]
	v_ashrrev_i32_e32 v4, 31, v21
	v_lshrrev_b32_e32 v4, 22, v4
	v_add_u32_e32 v4, v21, v4
	v_ashrrev_i32_e32 v5, 10, v4
	v_mul_i32_i24_e32 v4, 0x400, v5
	v_sub_u32_e32 v4, v21, v4
	v_lshrrev_b32_e32 v6, 4, v4
	v_bitop3_b32 v6, v6, v4, 32 bitop3:0x6c
	v_ashrrev_i32_e32 v7, 31, v6
	v_lshrrev_b32_e32 v7, 26, v7
	v_add_u32_e32 v7, v6, v7
	v_lshlrev_b32_e32 v4, 3, v5
	v_ashrrev_i32_e32 v10, 6, v7
	v_and_b32_e32 v7, 0xc0, v7
	v_and_b32_e32 v4, -16, v4
	v_lshlrev_b32_e32 v5, 5, v5
	v_sub_u32_e32 v6, v6, v7
	v_add_u32_e32 v4, v10, v4
	v_and_b32_e32 v5, 32, v5
	v_ashrrev_i16_sdwa v6, v144, sext(v6) dst_sel:DWORD dst_unused:UNUSED_PAD src0_sel:DWORD src1_sel:BYTE_0
	v_add_u32_sdwa v6, v5, sext(v6) dst_sel:DWORD dst_unused:UNUSED_PAD src0_sel:DWORD src1_sel:WORD_0
	v_ashrrev_i32_e32 v5, 31, v4
	v_lshlrev_b64 v[4:5], 11, v[4:5]
	s_ashr_i32 s43, s42, 31
	v_lshl_add_u64 v[10:11], s[46:47], 0, v[4:5]
	s_lshl_b64 s[46:47], s[42:43], 11
	v_add_u32_e32 v149, s33, v20
	s_add_u32 s48, s39, s46
	v_readfirstlane_b32 s41, v149
	v_add_u32_e32 v12, s33, v21
	s_addc_u32 s49, s50, s47
	s_mov_b32 m0, s41
	v_readfirstlane_b32 s41, v12
	v_lshl_add_u64 v[12:13], s[48:49], 0, v[0:1]
	v_lshl_add_u64 v[14:15], s[48:49], 0, v[4:5]
	s_or_b32 s48, s40, 0x80
	s_ashr_i32 s49, s48, 31
	s_lshl_b64 s[48:49], s[48:49], 11
	s_add_u32 s48, s51, s48
	v_ashrrev_i32_e32 v7, 31, v6
	s_addc_u32 s49, s52, s49
	v_lshlrev_b64 v[6:7], 1, v[6:7]
	v_add_u32_e32 v160, 0, v20
	v_lshl_add_u64 v[16:17], s[48:49], 0, v[0:1]
	v_lshl_add_u64 v[18:19], s[48:49], 0, v[4:5]
	s_or_b32 s48, s42, 0x80
	s_waitcnt lgkmcnt(0)
	s_barrier
	global_load_lds_dwordx4 v[8:9], off
	v_lshl_add_u64 v[10:11], v[10:11], 0, v[6:7]
	s_mov_b32 m0, s41
	v_readfirstlane_b32 s41, v160
	v_add_u32_e32 v161, 0x2000, v160
	s_ashr_i32 s49, s48, 31
	global_load_lds_dwordx4 v[10:11], off
	v_lshl_add_u64 v[12:13], v[12:13], 0, v[2:3]
	s_mov_b32 m0, s41
	v_readfirstlane_b32 s41, v161
	v_add_u32_e32 v163, s3, v20
	s_lshl_b64 s[48:49], s[48:49], 11
	global_load_lds_dwordx4 v[12:13], off
	v_lshl_add_u64 v[14:15], v[14:15], 0, v[6:7]
	s_mov_b32 m0, s41
	v_readfirstlane_b32 s41, v163
	v_add_u32_e32 v21, s3, v21
	s_add_u32 s48, s39, s48
	global_load_lds_dwordx4 v[14:15], off
	v_lshl_add_u64 v[16:17], v[16:17], 0, v[2:3]
	s_mov_b32 m0, s41
	v_readfirstlane_b32 s41, v21
	s_addc_u32 s49, s50, s49
	v_add_u32_e32 v164, 0x4000, v160
	global_load_lds_dwordx4 v[16:17], off
	v_lshl_add_u64 v[18:19], v[18:19], 0, v[6:7]
	s_mov_b32 m0, s41
	v_lshl_add_u64 v[22:23], s[48:49], 0, v[0:1]
	v_readfirstlane_b32 s41, v164
	v_add_u32_e32 v165, 0x6000, v160
	global_load_lds_dwordx4 v[18:19], off
	v_lshl_add_u64 v[132:133], v[22:23], 0, v[2:3]
	s_mov_b32 m0, s41
	v_lshl_add_u64 v[22:23], s[48:49], 0, v[4:5]
	v_readfirstlane_b32 s41, v165
	global_load_lds_dwordx4 v[132:133], off
	v_lshl_add_u64 v[134:135], v[22:23], 0, v[6:7]
	s_mov_b32 m0, s41
	v_ashrrev_i32_e32 v145, 8, v130
	global_load_lds_dwordx4 v[134:135], off
	v_cmp_eq_u32_e32 vcc, 1, v145
	s_and_saveexec_b64 s[48:49], vcc
	s_cbranch_execz .LBB0_573
	s_barrier

.LBB0_689:
	v_mov_b32_e32 v143, v154
	s_lshl_b32 s42, s56, 8
	v_ashrrev_i32_e32 v0, 31, v143
	v_lshrrev_b32_e32 v0, 26, v0
	v_add_u32_e32 v0, v143, v0
	v_ashrrev_i32_e32 v1, 6, v0
	v_bfe_i32 v0, v143, 27, 1
	v_lshlrev_b32_e32 v20, 4, v143
	v_lshrrev_b32_e32 v0, 22, v0
	v_add_u32_e32 v0, v20, v0
	v_and_b32_e32 v0, 0xfffffc00, v0
	v_sub_u32_e32 v0, v20, v0
	v_lshrrev_b32_e32 v2, 4, v0
	v_bitop3_b32 v2, v2, v0, 32 bitop3:0x6c
	v_ashrrev_i32_e32 v0, 31, v0
	v_lshrrev_b32_e32 v0, 26, v0
	v_lshlrev_b32_e32 v3, 3, v1
	v_add_u32_e32 v0, v2, v0
	v_and_b32_e32 v3, -16, v3
	v_ashrrev_i32_e32 v4, 6, v0
	v_add_u32_e32 v0, v4, v3
	v_mul_i32_i24_e32 v3, 64, v4
	s_ashr_i32 s43, s42, 31
	v_lshlrev_b32_e32 v1, 5, v1
	v_sub_u32_e32 v2, v2, v3
	s_lshl_b32 s30, s38, 8
	s_lshl_b64 s[38:39], s[42:43], 11
	v_and_b32_e32 v1, 32, v1
	v_ashrrev_i16_sdwa v2, v142, sext(v2) dst_sel:DWORD dst_unused:UNUSED_PAD src0_sel:DWORD src1_sel:BYTE_0
	s_add_u32 s40, s46, s38
	v_add_u32_sdwa v2, v1, sext(v2) dst_sel:DWORD dst_unused:UNUSED_PAD src0_sel:DWORD src1_sel:WORD_0
	v_ashrrev_i32_e32 v1, 31, v0
	s_addc_u32 s41, s47, s39
	v_lshlrev_b64 v[0:1], 11, v[0:1]
	v_ashrrev_i32_e32 v3, 31, v2
	v_lshl_add_u64 v[4:5], s[40:41], 0, v[0:1]
	v_lshlrev_b64 v[2:3], 1, v[2:3]
	v_add_u32_e32 v21, 0x2000, v20
	v_lshl_add_u64 v[8:9], v[4:5], 0, v[2:3]
	v_ashrrev_i32_e32 v4, 31, v21
	v_lshrrev_b32_e32 v4, 22, v4
	v_add_u32_e32 v4, v21, v4
	v_ashrrev_i32_e32 v5, 10, v4
	v_mul_i32_i24_e32 v4, 0x400, v5
	v_sub_u32_e32 v4, v21, v4
	v_lshrrev_b32_e32 v6, 4, v4
	v_bitop3_b32 v6, v6, v4, 32 bitop3:0x6c
	v_ashrrev_i32_e32 v7, 31, v6
	v_lshrrev_b32_e32 v7, 26, v7
	v_add_u32_e32 v7, v6, v7
	v_lshlrev_b32_e32 v4, 3, v5
	v_ashrrev_i32_e32 v10, 6, v7
	v_and_b32_e32 v7, 0xc0, v7
	v_add_u32_e32 v148, s33, v20
	v_and_b32_e32 v4, -16, v4
	v_lshlrev_b32_e32 v5, 5, v5
	v_sub_u32_e32 v6, v6, v7
	v_readfirstlane_b32 s31, v148
	v_add_u32_e32 v4, v10, v4
	v_and_b32_e32 v5, 32, v5
	v_ashrrev_i16_sdwa v6, v142, sext(v6) dst_sel:DWORD dst_unused:UNUSED_PAD src0_sel:DWORD src1_sel:BYTE_0
	v_add_u32_e32 v12, s33, v21
	s_mov_b32 m0, s31
	v_add_u32_sdwa v6, v5, sext(v6) dst_sel:DWORD dst_unused:UNUSED_PAD src0_sel:DWORD src1_sel:WORD_0
	v_ashrrev_i32_e32 v5, 31, v4
	v_readfirstlane_b32 s31, v12
	s_waitcnt lgkmcnt(0)
	s_barrier
	global_load_lds_dwordx4 v[8:9], off
	v_lshlrev_b64 v[4:5], 11, v[4:5]
	s_mov_b32 m0, s31
	s_ashr_i32 s31, s30, 31
	v_lshl_add_u64 v[10:11], s[40:41], 0, v[4:5]
	s_lshl_b64 s[40:41], s[30:31], 11
	s_add_u32 s62, s44, s40
	s_addc_u32 s63, s45, s41
	s_bitset1_b32 s42, 7
	s_ashr_i32 s43, s42, 31
	s_lshl_b64 s[42:43], s[42:43], 11
	s_add_u32 s42, s46, s42
	v_ashrrev_i32_e32 v7, 31, v6
	s_addc_u32 s43, s47, s43
	v_lshlrev_b64 v[6:7], 1, v[6:7]
	v_add_u32_e32 v159, 0, v20
	v_lshl_add_u64 v[16:17], s[42:43], 0, v[0:1]
	v_lshl_add_u64 v[18:19], s[42:43], 0, v[4:5]
	s_or_b32 s42, s30, 0x80
	v_lshl_add_u64 v[10:11], v[10:11], 0, v[6:7]
	v_lshl_add_u64 v[12:13], s[62:63], 0, v[0:1]
	v_readfirstlane_b32 s31, v159
	v_add_u32_e32 v160, 0x2000, v159
	s_ashr_i32 s43, s42, 31
	global_load_lds_dwordx4 v[10:11], off
	v_lshl_add_u64 v[12:13], v[12:13], 0, v[2:3]
	s_mov_b32 m0, s31
	v_lshl_add_u64 v[14:15], s[62:63], 0, v[4:5]
	v_readfirstlane_b32 s31, v160
	v_add_u32_e32 v162, s3, v20
	s_lshl_b64 s[42:43], s[42:43], 11
	global_load_lds_dwordx4 v[12:13], off
	v_lshl_add_u64 v[14:15], v[14:15], 0, v[6:7]
	s_mov_b32 m0, s31
	v_readfirstlane_b32 s31, v162
	v_add_u32_e32 v21, s3, v21
	s_add_u32 s42, s44, s42
	global_load_lds_dwordx4 v[14:15], off
	v_lshl_add_u64 v[16:17], v[16:17], 0, v[2:3]
	s_mov_b32 m0, s31
	v_readfirstlane_b32 s31, v21
	s_addc_u32 s43, s45, s43
	v_add_u32_e32 v163, 0x4000, v159
	global_load_lds_dwordx4 v[16:17], off
	v_lshl_add_u64 v[18:19], v[18:19], 0, v[6:7]
	s_mov_b32 m0, s31
	v_lshl_add_u64 v[22:23], s[42:43], 0, v[0:1]
	v_readfirstlane_b32 s31, v163
	v_add_u32_e32 v164, 0x6000, v159
	global_load_lds_dwordx4 v[18:19], off
	v_lshl_add_u64 v[130:131], v[22:23], 0, v[2:3]
	s_mov_b32 m0, s31
	v_lshl_add_u64 v[22:23], s[42:43], 0, v[4:5]
	v_readfirstlane_b32 s31, v164
	global_load_lds_dwordx4 v[130:131], off
	v_lshl_add_u64 v[132:133], v[22:23], 0, v[6:7]
	s_mov_b32 m0, s31
	v_ashrrev_i32_e32 v21, 8, v143
	global_load_lds_dwordx4 v[132:133], off
	v_cmp_eq_u32_e32 vcc, 1, v21
	s_and_saveexec_b64 s[42:43], vcc
	s_cbranch_execz .LBB0_691
	s_barrier

.LBB0_752:
	v_mov_b32_e32 v130, v154
	s_lshl_b32 s62, s42, 8
	v_bfe_i32 v1, v130, 27, 1
	v_lshlrev_b32_e32 v17, 4, v130
	v_lshrrev_b32_e32 v1, 22, v1
	v_add_u32_e32 v1, v17, v1
	v_and_b32_e32 v1, 0xfffffc00, v1
	v_ashrrev_i32_e32 v0, 31, v130
	v_sub_u32_e32 v1, v17, v1
	v_lshrrev_b32_e32 v0, 26, v0
	v_lshrrev_b32_e32 v2, 4, v1
	v_add_u32_e32 v0, v130, v0
	v_bitop3_b32 v2, v2, v1, 32 bitop3:0x6c
	v_ashrrev_i32_e32 v1, 31, v1
	v_ashrrev_i32_e32 v0, 6, v0
	v_lshrrev_b32_e32 v1, 26, v1
	v_lshlrev_b32_e32 v3, 3, v0
	v_add_u32_e32 v1, v2, v1
	v_and_b32_e32 v3, -16, v3
	v_ashrrev_i32_e32 v1, 6, v1
	v_add_u32_e32 v16, v1, v3
	v_mul_i32_i24_e32 v1, 64, v1
	v_lshlrev_b32_e32 v0, 5, v0
	v_sub_u32_e32 v1, v2, v1
	s_lshl_b32 s61, s40, 8
	s_mul_i32 s40, s40, 0x160000
	v_and_b32_e32 v0, 32, v0
	v_ashrrev_i16_sdwa v1, v148, sext(v1) dst_sel:DWORD dst_unused:UNUSED_PAD src0_sel:DWORD src1_sel:BYTE_0
	s_mul_hi_i32 s41, s61, 0x1600
	s_add_u32 s38, s47, s40
	v_add_u32_sdwa v132, v0, sext(v1) dst_sel:DWORD dst_unused:UNUSED_PAD src0_sel:DWORD src1_sel:WORD_0
	v_mad_i64_i32 v[134:135], s[44:45], v16, s53, 0
	s_addc_u32 s39, s48, s41
	v_lshlrev_b64 v[20:21], 1, v[134:135]
	v_ashrrev_i32_e32 v133, 31, v132
	v_lshl_add_u64 v[2:3], s[38:39], 0, v[20:21]
	v_lshlrev_b64 v[0:1], 1, v[132:133]
	v_add_u32_e32 v19, 0x2000, v17
	v_lshl_add_u64 v[4:5], v[2:3], 0, v[0:1]
	v_ashrrev_i32_e32 v2, 31, v19
	v_lshrrev_b32_e32 v2, 22, v2
	v_add_u32_e32 v2, v19, v2
	v_ashrrev_i32_e32 v2, 10, v2
	v_mul_i32_i24_e32 v3, 0x400, v2
	v_sub_u32_e32 v3, v19, v3
	v_lshrrev_b32_e32 v6, 4, v3
	v_bitop3_b32 v3, v6, v3, 32 bitop3:0x6c
	v_ashrrev_i32_e32 v7, 31, v3
	v_lshrrev_b32_e32 v7, 26, v7
	v_lshlrev_b32_e32 v6, 3, v2
	v_add_u32_e32 v7, v3, v7
	v_and_b32_e32 v6, -16, v6
	v_ashrrev_i32_e32 v8, 6, v7
	v_add_u32_e32 v18, v8, v6
	v_and_b32_e32 v6, 0xc0, v7
	v_add_u32_e32 v162, s33, v17
	v_lshlrev_b32_e32 v2, 5, v2
	v_sub_u32_e32 v3, v3, v6
	v_mad_i64_i32 v[138:139], s[44:45], v18, s53, 0
	v_readfirstlane_b32 s43, v162
	v_and_b32_e32 v2, 32, v2
	v_ashrrev_i16_sdwa v3, v148, sext(v3) dst_sel:DWORD dst_unused:UNUSED_PAD src0_sel:DWORD src1_sel:BYTE_0
	v_lshlrev_b64 v[22:23], 1, v[138:139]
	v_add_u32_e32 v8, s33, v19
	s_mov_b32 m0, s43
	v_add_u32_sdwa v136, v2, sext(v3) dst_sel:DWORD dst_unused:UNUSED_PAD src0_sel:DWORD src1_sel:WORD_0
	v_lshl_add_u64 v[6:7], s[38:39], 0, v[22:23]
	v_readfirstlane_b32 s38, v8
	s_mul_i32 s42, s42, 0x160000
	s_waitcnt lgkmcnt(0)
	s_barrier
	global_load_lds_dwordx4 v[4:5], off
	v_ashrrev_i32_e32 v137, 31, v136
	s_mov_b32 m0, s38
	s_mul_hi_i32 s43, s62, 0x1600
	s_add_u32 s38, s31, s42
	v_lshlrev_b64 v[2:3], 1, v[136:137]
	s_addc_u32 s39, s46, s43
	v_add_u32_e32 v164, 0, v17
	v_lshl_add_u64 v[6:7], v[6:7], 0, v[2:3]
	v_lshl_add_u64 v[8:9], s[38:39], 0, v[20:21]
	v_readfirstlane_b32 s44, v164
	v_add_u32_e32 v165, 0x2000, v164
	global_load_lds_dwordx4 v[6:7], off
	v_lshl_add_u64 v[8:9], v[8:9], 0, v[0:1]
	s_mov_b32 m0, s44
	v_lshl_add_u64 v[10:11], s[38:39], 0, v[22:23]
	v_readfirstlane_b32 s38, v165
	global_load_lds_dwordx4 v[8:9], off
	s_mov_b32 m0, s38
	s_or_b32 s38, s61, 0x80
	s_mul_hi_i32 s39, s38, 0x1600
	s_mulk_i32 s38, 0x1600
	s_add_u32 s38, s47, s38
	s_addc_u32 s39, s48, s39
	v_add_u32_e32 v167, s3, v17
	v_lshl_add_u64 v[10:11], v[10:11], 0, v[2:3]
	v_lshl_add_u64 v[12:13], s[38:39], 0, v[20:21]
	v_readfirstlane_b32 s44, v167
	v_add_u32_e32 v19, s3, v19
	global_load_lds_dwordx4 v[10:11], off
	v_lshl_add_u64 v[12:13], v[12:13], 0, v[0:1]
	s_mov_b32 m0, s44
	v_lshl_add_u64 v[14:15], s[38:39], 0, v[22:23]
	v_readfirstlane_b32 s38, v19
	global_load_lds_dwordx4 v[12:13], off
	s_mov_b32 m0, s38
	s_or_b32 s38, s62, 0x80
	s_mul_hi_i32 s39, s38, 0x1600
	s_mulk_i32 s38, 0x1600
	s_add_u32 s38, s31, s38
	s_addc_u32 s39, s46, s39
	v_add_u32_e32 v168, 0x4000, v164
	v_lshl_add_u64 v[14:15], v[14:15], 0, v[2:3]
	v_lshl_add_u64 v[20:21], s[38:39], 0, v[20:21]
	v_readfirstlane_b32 s44, v168
	global_load_lds_dwordx4 v[14:15], off
	v_lshl_add_u64 v[20:21], v[20:21], 0, v[0:1]
	s_mov_b32 m0, s44
	v_add_u32_e32 v169, 0x6000, v164
	global_load_lds_dwordx4 v[20:21], off
	v_lshl_add_u64 v[20:21], s[38:39], 0, v[22:23]
	v_readfirstlane_b32 s44, v169
	v_lshl_add_u64 v[20:21], v[20:21], 0, v[2:3]
	s_mov_b32 m0, s44
	v_ashrrev_i32_e32 v149, 8, v130
	global_load_lds_dwordx4 v[20:21], off
	v_cmp_eq_u32_e32 vcc, 1, v149
	s_and_saveexec_b64 s[44:45], vcc
	s_cbranch_execz .LBB0_754
	s_barrier

.LBB0_1685:
	v_mov_b32_e32 v130, v154
	s_lshl_b32 s40, s43, 8
	v_ashrrev_i32_e32 v0, 31, v130
	v_lshrrev_b32_e32 v0, 26, v0
	v_add_u32_e32 v0, v130, v0
	v_ashrrev_i32_e32 v1, 6, v0
	v_bfe_i32 v0, v130, 27, 1
	v_lshlrev_b32_e32 v20, 4, v130
	v_lshrrev_b32_e32 v0, 22, v0
	v_add_u32_e32 v0, v20, v0
	v_and_b32_e32 v0, 0xfffffc00, v0
	v_sub_u32_e32 v0, v20, v0
	v_lshrrev_b32_e32 v2, 4, v0
	v_bitop3_b32 v2, v2, v0, 32 bitop3:0x6c
	v_ashrrev_i32_e32 v0, 31, v0
	v_lshrrev_b32_e32 v0, 26, v0
	v_lshlrev_b32_e32 v3, 3, v1
	v_add_u32_e32 v0, v2, v0
	v_and_b32_e32 v3, -16, v3
	v_ashrrev_i32_e32 v4, 6, v0
	v_add_u32_e32 v0, v4, v3
	v_mul_i32_i24_e32 v3, 64, v4
	s_ashr_i32 s41, s40, 31
	v_lshlrev_b32_e32 v1, 5, v1
	v_sub_u32_e32 v2, v2, v3
	s_lshl_b32 s42, s42, 8
	s_lshl_b64 s[44:45], s[40:41], 11
	v_and_b32_e32 v1, 32, v1
	v_ashrrev_i16_sdwa v2, v144, sext(v2) dst_sel:DWORD dst_unused:UNUSED_PAD src0_sel:DWORD src1_sel:BYTE_0
	s_add_u32 s46, s51, s44
	v_add_u32_sdwa v2, v1, sext(v2) dst_sel:DWORD dst_unused:UNUSED_PAD src0_sel:DWORD src1_sel:WORD_0
	v_ashrrev_i32_e32 v1, 31, v0
	s_addc_u32 s47, s52, s45
	v_lshlrev_b64 v[0:1], 11, v[0:1]
	v_ashrrev_i32_e32 v3, 31, v2
	v_lshl_add_u64 v[4:5], s[46:47], 0, v[0:1]
	v_lshlrev_b64 v[2:3], 1, v[2:3]
	v_add_u32_e32 v21, 0x2000, v20
	v_lshl_add_u64 v[8:9], v[4:5], 0, v[2:3]
	v_ashrrev_i32_e32 v4, 31, v21
	v_lshrrev_b32_e32 v4, 22, v4
	v_add_u32_e32 v4, v21, v4
	v_ashrrev_i32_e32 v5, 10, v4
	v_mul_i32_i24_e32 v4, 0x400, v5
	v_sub_u32_e32 v4, v21, v4
	v_lshrrev_b32_e32 v6, 4, v4
	v_bitop3_b32 v6, v6, v4, 32 bitop3:0x6c
	v_ashrrev_i32_e32 v7, 31, v6
	v_lshrrev_b32_e32 v7, 26, v7
	v_add_u32_e32 v7, v6, v7
	v_lshlrev_b32_e32 v4, 3, v5
	v_ashrrev_i32_e32 v10, 6, v7
	v_and_b32_e32 v7, 0xc0, v7
	v_and_b32_e32 v4, -16, v4
	v_lshlrev_b32_e32 v5, 5, v5
	v_sub_u32_e32 v6, v6, v7
	v_add_u32_e32 v4, v10, v4
	v_and_b32_e32 v5, 32, v5
	v_ashrrev_i16_sdwa v6, v144, sext(v6) dst_sel:DWORD dst_unused:UNUSED_PAD src0_sel:DWORD src1_sel:BYTE_0
	v_add_u32_sdwa v6, v5, sext(v6) dst_sel:DWORD dst_unused:UNUSED_PAD src0_sel:DWORD src1_sel:WORD_0
	v_ashrrev_i32_e32 v5, 31, v4
	v_lshlrev_b64 v[4:5], 11, v[4:5]
	s_ashr_i32 s43, s42, 31
	v_lshl_add_u64 v[10:11], s[46:47], 0, v[4:5]
	s_lshl_b64 s[46:47], s[42:43], 11
	v_add_u32_e32 v156, s33, v20
	s_add_u32 s48, s39, s46
	v_readfirstlane_b32 s41, v156
	v_add_u32_e32 v12, s33, v21
	s_addc_u32 s49, s50, s47
	s_mov_b32 m0, s41
	v_readfirstlane_b32 s41, v12
	v_lshl_add_u64 v[12:13], s[48:49], 0, v[0:1]
	v_lshl_add_u64 v[14:15], s[48:49], 0, v[4:5]
	s_or_b32 s48, s40, 0x80
	s_ashr_i32 s49, s48, 31
	s_lshl_b64 s[48:49], s[48:49], 11
	s_add_u32 s48, s51, s48
	v_ashrrev_i32_e32 v7, 31, v6
	s_addc_u32 s49, s52, s49
	v_lshlrev_b64 v[6:7], 1, v[6:7]
	v_add_u32_e32 v162, 0, v20
	v_lshl_add_u64 v[16:17], s[48:49], 0, v[0:1]
	v_lshl_add_u64 v[18:19], s[48:49], 0, v[4:5]
	s_or_b32 s48, s42, 0x80
	s_waitcnt lgkmcnt(0)
	s_barrier
	global_load_lds_dwordx4 v[8:9], off
	v_lshl_add_u64 v[10:11], v[10:11], 0, v[6:7]
	s_mov_b32 m0, s41
	v_readfirstlane_b32 s41, v162
	v_add_u32_e32 v163, 0x2000, v162
	s_ashr_i32 s49, s48, 31
	global_load_lds_dwordx4 v[10:11], off
	v_lshl_add_u64 v[12:13], v[12:13], 0, v[2:3]
	s_mov_b32 m0, s41
	v_readfirstlane_b32 s41, v163
	v_add_u32_e32 v165, s3, v20
	s_lshl_b64 s[48:49], s[48:49], 11
	global_load_lds_dwordx4 v[12:13], off
	v_lshl_add_u64 v[14:15], v[14:15], 0, v[6:7]
	s_mov_b32 m0, s41
	v_readfirstlane_b32 s41, v165
	v_add_u32_e32 v21, s3, v21
	s_add_u32 s48, s39, s48
	global_load_lds_dwordx4 v[14:15], off
	v_lshl_add_u64 v[16:17], v[16:17], 0, v[2:3]
	s_mov_b32 m0, s41
	v_readfirstlane_b32 s41, v21
	s_addc_u32 s49, s50, s49
	v_add_u32_e32 v166, 0x4000, v162
	global_load_lds_dwordx4 v[16:17], off
	v_lshl_add_u64 v[18:19], v[18:19], 0, v[6:7]
	s_mov_b32 m0, s41
	v_lshl_add_u64 v[22:23], s[48:49], 0, v[0:1]
	v_readfirstlane_b32 s41, v166
	v_add_u32_e32 v167, 0x6000, v162
	global_load_lds_dwordx4 v[18:19], off
	v_lshl_add_u64 v[132:133], v[22:23], 0, v[2:3]
	s_mov_b32 m0, s41
	v_lshl_add_u64 v[22:23], s[48:49], 0, v[4:5]
	v_readfirstlane_b32 s41, v167
	global_load_lds_dwordx4 v[132:133], off
	v_lshl_add_u64 v[134:135], v[22:23], 0, v[6:7]
	s_mov_b32 m0, s41
	v_ashrrev_i32_e32 v145, 8, v130
	global_load_lds_dwordx4 v[134:135], off
	v_cmp_eq_u32_e32 vcc, 1, v145
	s_and_saveexec_b64 s[48:49], vcc
	s_cbranch_execz .LBB0_1687
	s_barrier

.LBB0_1803:
	v_mov_b32_e32 v143, v154
	s_lshl_b32 s42, s56, 8
	v_ashrrev_i32_e32 v0, 31, v143
	v_lshrrev_b32_e32 v0, 26, v0
	v_add_u32_e32 v0, v143, v0
	v_ashrrev_i32_e32 v1, 6, v0
	v_bfe_i32 v0, v143, 27, 1
	v_lshlrev_b32_e32 v20, 4, v143
	v_lshrrev_b32_e32 v0, 22, v0
	v_add_u32_e32 v0, v20, v0
	v_and_b32_e32 v0, 0xfffffc00, v0
	v_sub_u32_e32 v0, v20, v0
	v_lshrrev_b32_e32 v2, 4, v0
	v_bitop3_b32 v2, v2, v0, 32 bitop3:0x6c
	v_ashrrev_i32_e32 v0, 31, v0
	v_lshrrev_b32_e32 v0, 26, v0
	v_lshlrev_b32_e32 v3, 3, v1
	v_add_u32_e32 v0, v2, v0
	v_and_b32_e32 v3, -16, v3
	v_ashrrev_i32_e32 v4, 6, v0
	v_add_u32_e32 v0, v4, v3
	v_mul_i32_i24_e32 v3, 64, v4
	s_ashr_i32 s43, s42, 31
	v_lshlrev_b32_e32 v1, 5, v1
	v_sub_u32_e32 v2, v2, v3
	s_lshl_b32 s30, s38, 8
	s_lshl_b64 s[38:39], s[42:43], 11
	v_and_b32_e32 v1, 32, v1
	v_ashrrev_i16_sdwa v2, v142, sext(v2) dst_sel:DWORD dst_unused:UNUSED_PAD src0_sel:DWORD src1_sel:BYTE_0
	s_add_u32 s40, s46, s38
	v_add_u32_sdwa v2, v1, sext(v2) dst_sel:DWORD dst_unused:UNUSED_PAD src0_sel:DWORD src1_sel:WORD_0
	v_ashrrev_i32_e32 v1, 31, v0
	s_addc_u32 s41, s47, s39
	v_lshlrev_b64 v[0:1], 11, v[0:1]
	v_ashrrev_i32_e32 v3, 31, v2
	v_lshl_add_u64 v[4:5], s[40:41], 0, v[0:1]
	v_lshlrev_b64 v[2:3], 1, v[2:3]
	v_add_u32_e32 v21, 0x2000, v20
	v_lshl_add_u64 v[8:9], v[4:5], 0, v[2:3]
	v_ashrrev_i32_e32 v4, 31, v21
	v_lshrrev_b32_e32 v4, 22, v4
	v_add_u32_e32 v4, v21, v4
	v_ashrrev_i32_e32 v5, 10, v4
	v_mul_i32_i24_e32 v4, 0x400, v5
	v_sub_u32_e32 v4, v21, v4
	v_lshrrev_b32_e32 v6, 4, v4
	v_bitop3_b32 v6, v6, v4, 32 bitop3:0x6c
	v_ashrrev_i32_e32 v7, 31, v6
	v_lshrrev_b32_e32 v7, 26, v7
	v_add_u32_e32 v7, v6, v7
	v_lshlrev_b32_e32 v4, 3, v5
	v_ashrrev_i32_e32 v10, 6, v7
	v_and_b32_e32 v7, 0xc0, v7
	v_add_u32_e32 v155, s33, v20
	v_and_b32_e32 v4, -16, v4
	v_lshlrev_b32_e32 v5, 5, v5
	v_sub_u32_e32 v6, v6, v7
	v_readfirstlane_b32 s31, v155
	v_add_u32_e32 v4, v10, v4
	v_and_b32_e32 v5, 32, v5
	v_ashrrev_i16_sdwa v6, v142, sext(v6) dst_sel:DWORD dst_unused:UNUSED_PAD src0_sel:DWORD src1_sel:BYTE_0
	v_add_u32_e32 v12, s33, v21
	s_mov_b32 m0, s31
	v_add_u32_sdwa v6, v5, sext(v6) dst_sel:DWORD dst_unused:UNUSED_PAD src0_sel:DWORD src1_sel:WORD_0
	v_ashrrev_i32_e32 v5, 31, v4
	v_readfirstlane_b32 s31, v12
	s_waitcnt lgkmcnt(0)
	s_barrier
	global_load_lds_dwordx4 v[8:9], off
	v_lshlrev_b64 v[4:5], 11, v[4:5]
	s_mov_b32 m0, s31
	s_ashr_i32 s31, s30, 31
	v_lshl_add_u64 v[10:11], s[40:41], 0, v[4:5]
	s_lshl_b64 s[40:41], s[30:31], 11
	s_add_u32 s62, s44, s40
	s_addc_u32 s63, s45, s41
	s_bitset1_b32 s42, 7
	s_ashr_i32 s43, s42, 31
	s_lshl_b64 s[42:43], s[42:43], 11
	s_add_u32 s42, s46, s42
	v_ashrrev_i32_e32 v7, 31, v6
	s_addc_u32 s43, s47, s43
	v_lshlrev_b64 v[6:7], 1, v[6:7]
	v_add_u32_e32 v161, 0, v20
	v_lshl_add_u64 v[16:17], s[42:43], 0, v[0:1]
	v_lshl_add_u64 v[18:19], s[42:43], 0, v[4:5]
	s_or_b32 s42, s30, 0x80
	v_lshl_add_u64 v[10:11], v[10:11], 0, v[6:7]
	v_lshl_add_u64 v[12:13], s[62:63], 0, v[0:1]
	v_readfirstlane_b32 s31, v161
	v_add_u32_e32 v162, 0x2000, v161
	s_ashr_i32 s43, s42, 31
	global_load_lds_dwordx4 v[10:11], off
	v_lshl_add_u64 v[12:13], v[12:13], 0, v[2:3]
	s_mov_b32 m0, s31
	v_lshl_add_u64 v[14:15], s[62:63], 0, v[4:5]
	v_readfirstlane_b32 s31, v162
	v_add_u32_e32 v164, s3, v20
	s_lshl_b64 s[42:43], s[42:43], 11
	global_load_lds_dwordx4 v[12:13], off
	v_lshl_add_u64 v[14:15], v[14:15], 0, v[6:7]
	s_mov_b32 m0, s31
	v_readfirstlane_b32 s31, v164
	v_add_u32_e32 v21, s3, v21
	s_add_u32 s42, s44, s42
	global_load_lds_dwordx4 v[14:15], off
	v_lshl_add_u64 v[16:17], v[16:17], 0, v[2:3]
	s_mov_b32 m0, s31
	v_readfirstlane_b32 s31, v21
	s_addc_u32 s43, s45, s43
	v_add_u32_e32 v165, 0x4000, v161
	global_load_lds_dwordx4 v[16:17], off
	v_lshl_add_u64 v[18:19], v[18:19], 0, v[6:7]
	s_mov_b32 m0, s31
	v_lshl_add_u64 v[22:23], s[42:43], 0, v[0:1]
	v_readfirstlane_b32 s31, v165
	v_add_u32_e32 v166, 0x6000, v161
	global_load_lds_dwordx4 v[18:19], off
	v_lshl_add_u64 v[130:131], v[22:23], 0, v[2:3]
	s_mov_b32 m0, s31
	v_lshl_add_u64 v[22:23], s[42:43], 0, v[4:5]
	v_readfirstlane_b32 s31, v166
	global_load_lds_dwordx4 v[130:131], off
	v_lshl_add_u64 v[132:133], v[22:23], 0, v[6:7]
	s_mov_b32 m0, s31
	v_ashrrev_i32_e32 v21, 8, v143
	global_load_lds_dwordx4 v[132:133], off
	v_cmp_eq_u32_e32 vcc, 1, v21
	s_and_saveexec_b64 s[42:43], vcc
	s_cbranch_execz .LBB0_1805
	s_barrier

.LBB0_1866:
	v_mov_b32_e32 v128, v154
	s_lshl_b32 s61, s42, 8
	v_bfe_i32 v1, v128, 27, 1
	v_lshlrev_b32_e32 v17, 4, v128
	v_lshrrev_b32_e32 v1, 22, v1
	v_add_u32_e32 v1, v17, v1
	v_and_b32_e32 v1, 0xfffffc00, v1
	v_ashrrev_i32_e32 v0, 31, v128
	v_sub_u32_e32 v1, v17, v1
	v_lshrrev_b32_e32 v0, 26, v0
	v_lshrrev_b32_e32 v2, 4, v1
	v_add_u32_e32 v0, v128, v0
	v_bitop3_b32 v2, v2, v1, 32 bitop3:0x6c
	v_ashrrev_i32_e32 v1, 31, v1
	v_ashrrev_i32_e32 v0, 6, v0
	v_lshrrev_b32_e32 v1, 26, v1
	v_lshlrev_b32_e32 v3, 3, v0
	v_add_u32_e32 v1, v2, v1
	v_and_b32_e32 v3, -16, v3
	v_ashrrev_i32_e32 v1, 6, v1
	v_add_u32_e32 v16, v1, v3
	v_mul_i32_i24_e32 v1, 64, v1
	v_lshlrev_b32_e32 v0, 5, v0
	v_sub_u32_e32 v1, v2, v1
	s_lshl_b32 s60, s40, 8
	s_mul_i32 s40, s40, 0x160000
	v_and_b32_e32 v0, 32, v0
	v_ashrrev_i16_sdwa v1, v152, sext(v1) dst_sel:DWORD dst_unused:UNUSED_PAD src0_sel:DWORD src1_sel:BYTE_0
	s_mul_hi_i32 s41, s60, 0x1600
	s_add_u32 s38, s47, s40
	v_add_u32_sdwa v130, v0, sext(v1) dst_sel:DWORD dst_unused:UNUSED_PAD src0_sel:DWORD src1_sel:WORD_0
	v_mad_i64_i32 v[132:133], s[44:45], v16, s53, 0
	s_addc_u32 s39, s48, s41
	v_lshlrev_b64 v[20:21], 1, v[132:133]
	v_ashrrev_i32_e32 v131, 31, v130
	v_lshl_add_u64 v[2:3], s[38:39], 0, v[20:21]
	v_lshlrev_b64 v[0:1], 1, v[130:131]
	v_add_u32_e32 v19, 0x2000, v17
	v_lshl_add_u64 v[4:5], v[2:3], 0, v[0:1]
	v_ashrrev_i32_e32 v2, 31, v19
	v_lshrrev_b32_e32 v2, 22, v2
	v_add_u32_e32 v2, v19, v2
	v_ashrrev_i32_e32 v2, 10, v2
	v_mul_i32_i24_e32 v3, 0x400, v2
	v_sub_u32_e32 v3, v19, v3
	v_lshrrev_b32_e32 v6, 4, v3
	v_bitop3_b32 v3, v6, v3, 32 bitop3:0x6c
	v_ashrrev_i32_e32 v7, 31, v3
	v_lshrrev_b32_e32 v7, 26, v7
	v_lshlrev_b32_e32 v6, 3, v2
	v_add_u32_e32 v7, v3, v7
	v_and_b32_e32 v6, -16, v6
	v_ashrrev_i32_e32 v8, 6, v7
	v_add_u32_e32 v18, v8, v6
	v_and_b32_e32 v6, 0xc0, v7
	v_add_u32_e32 v162, s33, v17
	v_lshlrev_b32_e32 v2, 5, v2
	v_sub_u32_e32 v3, v3, v6
	v_mad_i64_i32 v[136:137], s[44:45], v18, s53, 0
	v_readfirstlane_b32 s43, v162
	v_and_b32_e32 v2, 32, v2
	v_ashrrev_i16_sdwa v3, v152, sext(v3) dst_sel:DWORD dst_unused:UNUSED_PAD src0_sel:DWORD src1_sel:BYTE_0
	v_lshlrev_b64 v[22:23], 1, v[136:137]
	v_add_u32_e32 v8, s33, v19
	s_mov_b32 m0, s43
	v_add_u32_sdwa v134, v2, sext(v3) dst_sel:DWORD dst_unused:UNUSED_PAD src0_sel:DWORD src1_sel:WORD_0
	v_lshl_add_u64 v[6:7], s[38:39], 0, v[22:23]
	v_readfirstlane_b32 s38, v8
	s_mul_i32 s42, s42, 0x160000
	s_waitcnt lgkmcnt(0)
	s_barrier
	global_load_lds_dwordx4 v[4:5], off
	v_ashrrev_i32_e32 v135, 31, v134
	s_mov_b32 m0, s38
	s_mul_hi_i32 s43, s61, 0x1600
	s_add_u32 s38, s31, s42
	v_lshlrev_b64 v[2:3], 1, v[134:135]
	s_addc_u32 s39, s46, s43
	v_add_u32_e32 v164, 0, v17
	v_lshl_add_u64 v[6:7], v[6:7], 0, v[2:3]
	v_lshl_add_u64 v[8:9], s[38:39], 0, v[20:21]
	v_readfirstlane_b32 s44, v164
	v_add_u32_e32 v165, 0x2000, v164
	global_load_lds_dwordx4 v[6:7], off
	v_lshl_add_u64 v[8:9], v[8:9], 0, v[0:1]
	s_mov_b32 m0, s44
	v_lshl_add_u64 v[10:11], s[38:39], 0, v[22:23]
	v_readfirstlane_b32 s38, v165
	global_load_lds_dwordx4 v[8:9], off
	s_mov_b32 m0, s38
	s_or_b32 s38, s60, 0x80
	s_mul_hi_i32 s39, s38, 0x1600
	s_mulk_i32 s38, 0x1600
	s_add_u32 s38, s47, s38
	s_addc_u32 s39, s48, s39
	v_add_u32_e32 v167, s3, v17
	v_lshl_add_u64 v[10:11], v[10:11], 0, v[2:3]
	v_lshl_add_u64 v[12:13], s[38:39], 0, v[20:21]
	v_readfirstlane_b32 s44, v167
	v_add_u32_e32 v19, s3, v19
	global_load_lds_dwordx4 v[10:11], off
	v_lshl_add_u64 v[12:13], v[12:13], 0, v[0:1]
	s_mov_b32 m0, s44
	v_lshl_add_u64 v[14:15], s[38:39], 0, v[22:23]
	v_readfirstlane_b32 s38, v19
	global_load_lds_dwordx4 v[12:13], off
	s_mov_b32 m0, s38
	s_or_b32 s38, s61, 0x80
	s_mul_hi_i32 s39, s38, 0x1600
	s_mulk_i32 s38, 0x1600
	s_add_u32 s38, s31, s38
	s_addc_u32 s39, s46, s39
	v_add_u32_e32 v168, 0x4000, v164
	v_lshl_add_u64 v[14:15], v[14:15], 0, v[2:3]
	v_lshl_add_u64 v[20:21], s[38:39], 0, v[20:21]
	v_readfirstlane_b32 s44, v168
	global_load_lds_dwordx4 v[14:15], off
	v_lshl_add_u64 v[20:21], v[20:21], 0, v[0:1]
	s_mov_b32 m0, s44
	v_add_u32_e32 v169, 0x6000, v164
	global_load_lds_dwordx4 v[20:21], off
	v_lshl_add_u64 v[20:21], s[38:39], 0, v[22:23]
	v_readfirstlane_b32 s44, v169
	v_lshl_add_u64 v[20:21], v[20:21], 0, v[2:3]
	s_mov_b32 m0, s44
	v_ashrrev_i32_e32 v153, 8, v128
	global_load_lds_dwordx4 v[20:21], off
	v_cmp_eq_u32_e32 vcc, 1, v153
	s_and_saveexec_b64 s[44:45], vcc
	s_cbranch_execz .LBB0_1868
	s_barrier
